# s7 + gridDim==512 guards around the fused sub3->sub4 sync (falls back to the grid barrier for any other grid)
# baseline (speedup 1.0000x reference)
.LBB0_148:
	s_and_b32 s0, s14, -8
	s_or_b32 s0, s0, s15
	s_load_dword s22, s[96:97], 0x0
	s_waitcnt lgkmcnt(0)
	s_cmp_eq_u32 s22, 0x200
	s_cbranch_scc0 .Lgw_skipall
	v_cmp_eq_u32_e64 s[22:23], 0, v124
	s_and_saveexec_b64 s[20:21], s[22:23]
	s_cbranch_execz .Lgw_done
	s_lshl_b32 s22, s0, 2
	s_lshl_b32 s23, s12, 8
	s_add_i32 s22, s22, s23
	s_addk_i32 s22, 0x1404
	v_mov_b32_e32 v0, s22
	s_mov_b32 s23, 0

.Lgw_skipall:
	s_ashr_i32 s1, s0, 31
	s_lshl_b64 s[22:23], s[0:1], 18
	v_readfirstlane_b32 s43, v101
	v_add_u32_e32 v84, 0x400, v101
	s_and_b32 s20, s18, 0x380
	v_lshl_add_u64 v[64:65], v[96:97], 0, s[22:23]
	s_mov_b32 m0, s43
	s_mov_b64 s[22:23], 0x400
	v_readfirstlane_b32 s41, v84
	v_add_u32_e32 v85, 0x2000, v101
	s_lshl_b32 s30, s20, 11
	global_load_lds_dwordx4 v[64:65], off
	s_waitcnt lgkmcnt(0)
	v_lshl_add_u64 v[0:1], v[64:65], 0, s[22:23]
	s_mov_b32 m0, s41
	v_readfirstlane_b32 s42, v85
	v_add_u32_e32 v86, 0x2400, v101
	v_lshl_add_u64 v[66:67], v[98:99], 0, s[30:31]
	global_load_lds_dwordx4 v[0:1], off
	s_mov_b32 m0, s42
	v_readfirstlane_b32 s48, v86
	v_add_u32_e32 v80, 0x4000, v101
	global_load_lds_dwordx4 v[66:67], off
	v_lshl_add_u64 v[0:1], v[66:67], 0, s[22:23]
	s_mov_b32 m0, s48
	v_readfirstlane_b32 s38, v80
	v_add_u32_e32 v81, 0x4400, v101
	global_load_lds_dwordx4 v[0:1], off
	v_lshl_add_u64 v[0:1], v[64:65], 0, s[44:45]
	s_mov_b32 m0, s38
	v_readfirstlane_b32 s37, v81
	v_add_u32_e32 v82, 0x6000, v101
	global_load_lds_dwordx4 v[0:1], off
	v_lshl_add_u64 v[0:1], v[64:65], 0, s[66:67]
	s_mov_b32 m0, s37
	v_readfirstlane_b32 s39, v82
	v_add_u32_e32 v83, 0x6400, v101
	global_load_lds_dwordx4 v[0:1], off
	v_lshl_add_u64 v[0:1], v[66:67], 0, s[44:45]
	s_mov_b32 m0, s39
	v_readfirstlane_b32 s40, v83
	v_add_u32_e32 v76, 0x8000, v101
	global_load_lds_dwordx4 v[0:1], off
	v_lshl_add_u64 v[0:1], v[66:67], 0, s[66:67]
	s_mov_b32 m0, s40
	v_readfirstlane_b32 s34, v76
	v_add_u32_e32 v77, 0x8400, v101
	global_load_lds_dwordx4 v[0:1], off
	v_lshl_add_u64 v[0:1], v[64:65], 0, s[28:29]
	s_mov_b32 m0, s34
	s_mov_b64 s[22:23], 0x4400
	v_readfirstlane_b32 s30, v77
	v_add_u32_e32 v78, 0xa000, v101
	global_load_lds_dwordx4 v[0:1], off
	v_lshl_add_u64 v[0:1], v[64:65], 0, s[22:23]
	s_mov_b32 m0, s30
	v_readfirstlane_b32 s35, v78
	v_add_u32_e32 v79, 0xa400, v101
	global_load_lds_dwordx4 v[0:1], off
	v_lshl_add_u64 v[0:1], v[66:67], 0, s[28:29]
	s_mov_b32 m0, s35
	v_readfirstlane_b32 s36, v79
	global_load_lds_dwordx4 v[0:1], off
	v_lshl_add_u64 v[0:1], v[66:67], 0, s[22:23]
	s_mov_b32 m0, s36
	v_add_u32_e32 v68, v125, v121
	global_load_lds_dwordx4 v[0:1], off
	s_waitcnt vmcnt(8)
	v_add_u32_e32 v69, v122, v121
	v_add_u32_e32 v70, v125, v119
	v_add_u32_e32 v71, v122, v119
	s_waitcnt lgkmcnt(0)
	s_barrier
	ds_read_b128 v[0:3], v68
	ds_read_b128 v[16:19], v68 offset:2048
	ds_read_b128 v[4:7], v69 offset:8192
	ds_read_b128 v[20:23], v69 offset:10240
	ds_read_b128 v[88:91], v70
	ds_read_b128 v[92:95], v70 offset:2048
	ds_read_b128 v[152:155], v71 offset:8192
	ds_read_b128 v[156:159], v71 offset:10240
	s_mov_b64 s[22:23], 0x6000
	v_add_u32_e32 v72, 0xc000, v101
	v_lshl_add_u64 v[8:9], v[66:67], 0, s[22:23]
	v_lshl_add_u64 v[14:15], v[64:65], 0, s[22:23]
	v_readfirstlane_b32 s22, v72
	v_add_u32_e32 v73, 0xc400, v101
	s_mov_b64 s[64:65], 0x6400
	s_mov_b32 m0, s22
	v_readfirstlane_b32 s1, v73
	v_add_u32_e32 v74, 0xe000, v101
	v_lshl_add_u64 v[12:13], v[64:65], 0, s[64:65]
	global_load_lds_dwordx4 v[14:15], off
	s_mov_b32 m0, s1
	v_readfirstlane_b32 s21, v74
	v_add_u32_e32 v75, 0xe400, v101
	global_load_lds_dwordx4 v[12:13], off
	s_mov_b32 m0, s21
	v_readfirstlane_b32 s23, v75
	v_lshl_add_u64 v[10:11], v[66:67], 0, s[64:65]
	global_load_lds_dwordx4 v[8:9], off
	s_mov_b32 m0, s23
	s_nop 0
	global_load_lds_dwordx4 v[10:11], off
	s_waitcnt lgkmcnt(0)
	v_mfma_f32_32x32x16_bf16 v[32:47], v[0:3], v[4:7], 0
	s_waitcnt vmcnt(8)
	s_waitcnt lgkmcnt(0)
	s_barrier
	v_mfma_f32_32x32x16_bf16 v[48:63], v[0:3], v[20:23], 0
	v_mfma_f32_32x32x16_bf16 v[0:15], v[16:19], v[4:7], 0
	v_mfma_f32_32x32x16_bf16 v[16:31], v[16:19], v[20:23], 0
	v_mfma_f32_32x32x16_bf16 v[32:47], v[88:91], v[152:155], v[32:47]
	v_mfma_f32_32x32x16_bf16 v[48:63], v[88:91], v[156:159], v[48:63]
	v_mfma_f32_32x32x16_bf16 v[0:15], v[92:95], v[152:155], v[0:15]
	v_mfma_f32_32x32x16_bf16 v[16:31], v[92:95], v[156:159], v[16:31]
	ds_read_b128 v[88:91], v68 offset:16384
	ds_read_b128 v[92:95], v68 offset:18432
	ds_read_b128 v[152:155], v69 offset:24576
	ds_read_b128 v[156:159], v69 offset:26624
	ds_read_b128 v[160:163], v70 offset:16384
	ds_read_b128 v[164:167], v70 offset:18432
	ds_read_b128 v[168:171], v71 offset:24576
	ds_read_b128 v[172:175], v71 offset:26624
	s_mov_b64 s[64:65], 0x8000
	s_mov_b32 m0, s43
	s_mov_b64 s[68:69], 0x8400
	v_lshl_add_u64 v[182:183], v[64:65], 0, s[64:65]
	v_lshl_add_u64 v[180:181], v[64:65], 0, s[68:69]
	global_load_lds_dwordx4 v[182:183], off
	s_mov_b32 m0, s41
	v_lshl_add_u64 v[176:177], v[66:67], 0, s[64:65]
	global_load_lds_dwordx4 v[180:181], off
	s_mov_b32 m0, s42
	v_lshl_add_u64 v[178:179], v[66:67], 0, s[68:69]
	global_load_lds_dwordx4 v[176:177], off
	s_mov_b32 m0, s48
	s_nop 0
	global_load_lds_dwordx4 v[178:179], off
	s_waitcnt lgkmcnt(0)
	v_mfma_f32_32x32x16_bf16 v[32:47], v[88:91], v[152:155], v[32:47]
	s_waitcnt vmcnt(8)
	s_waitcnt lgkmcnt(0)
	s_barrier
	v_mfma_f32_32x32x16_bf16 v[48:63], v[88:91], v[156:159], v[48:63]
	v_mfma_f32_32x32x16_bf16 v[0:15], v[92:95], v[152:155], v[0:15]
	v_mfma_f32_32x32x16_bf16 v[16:31], v[92:95], v[156:159], v[16:31]
	v_mfma_f32_32x32x16_bf16 v[32:47], v[160:163], v[168:171], v[32:47]
	v_mfma_f32_32x32x16_bf16 v[48:63], v[160:163], v[172:175], v[48:63]
	v_mfma_f32_32x32x16_bf16 v[0:15], v[164:167], v[168:171], v[0:15]
	v_mfma_f32_32x32x16_bf16 v[16:31], v[164:167], v[172:175], v[16:31]
	ds_read_b128 v[88:91], v68 offset:32768
	ds_read_b128 v[92:95], v68 offset:34816
	ds_read_b128 v[152:155], v69 offset:40960
	ds_read_b128 v[156:159], v69 offset:43008
	ds_read_b128 v[160:163], v70 offset:32768
	ds_read_b128 v[164:167], v70 offset:34816
	ds_read_b128 v[168:171], v71 offset:40960
	ds_read_b128 v[172:175], v71 offset:43008
	s_mov_b64 s[64:65], 0xa000
	s_mov_b32 m0, s38
	s_mov_b64 s[68:69], 0xa400
	v_lshl_add_u64 v[182:183], v[64:65], 0, s[64:65]
	v_lshl_add_u64 v[180:181], v[64:65], 0, s[68:69]
	global_load_lds_dwordx4 v[182:183], off
	s_mov_b32 m0, s37
	v_lshl_add_u64 v[176:177], v[66:67], 0, s[64:65]
	global_load_lds_dwordx4 v[180:181], off
	s_mov_b32 m0, s39
	v_lshl_add_u64 v[178:179], v[66:67], 0, s[68:69]
	global_load_lds_dwordx4 v[176:177], off
	s_mov_b32 m0, s40
	s_nop 0
	global_load_lds_dwordx4 v[178:179], off
	s_waitcnt lgkmcnt(0)
	v_mfma_f32_32x32x16_bf16 v[32:47], v[88:91], v[152:155], v[32:47]
	s_waitcnt vmcnt(8)
	s_waitcnt lgkmcnt(0)
	s_barrier
	v_mfma_f32_32x32x16_bf16 v[48:63], v[88:91], v[156:159], v[48:63]
	v_mfma_f32_32x32x16_bf16 v[0:15], v[92:95], v[152:155], v[0:15]
	v_mfma_f32_32x32x16_bf16 v[16:31], v[92:95], v[156:159], v[16:31]
	v_mfma_f32_32x32x16_bf16 v[32:47], v[160:163], v[168:171], v[32:47]
	v_mfma_f32_32x32x16_bf16 v[48:63], v[160:163], v[172:175], v[48:63]
	v_mfma_f32_32x32x16_bf16 v[0:15], v[164:167], v[168:171], v[0:15]
	v_mfma_f32_32x32x16_bf16 v[16:31], v[164:167], v[172:175], v[16:31]
	ds_read_b128 v[88:91], v68 offset:49152
	ds_read_b128 v[92:95], v68 offset:51200
	ds_read_b128 v[152:155], v69 offset:57344
	ds_read_b128 v[156:159], v69 offset:59392
	ds_read_b128 v[160:163], v70 offset:49152
	ds_read_b128 v[164:167], v70 offset:51200
	ds_read_b128 v[168:171], v71 offset:57344
	ds_read_b128 v[172:175], v71 offset:59392
	s_mov_b64 s[64:65], 0xc000
	s_mov_b32 m0, s34
	s_mov_b64 s[68:69], 0xc400
	v_lshl_add_u64 v[182:183], v[64:65], 0, s[64:65]
	v_lshl_add_u64 v[180:181], v[64:65], 0, s[68:69]
	global_load_lds_dwordx4 v[182:183], off
	s_mov_b32 m0, s30
	v_lshl_add_u64 v[176:177], v[66:67], 0, s[64:65]
	global_load_lds_dwordx4 v[180:181], off
	s_mov_b32 m0, s35
	v_lshl_add_u64 v[178:179], v[66:67], 0, s[68:69]
	global_load_lds_dwordx4 v[176:177], off
	s_mov_b32 m0, s36
	s_nop 0
	global_load_lds_dwordx4 v[178:179], off
	s_waitcnt lgkmcnt(0)
	v_mfma_f32_32x32x16_bf16 v[32:47], v[88:91], v[152:155], v[32:47]
	s_waitcnt vmcnt(8)
	s_waitcnt lgkmcnt(0)
	s_barrier
	v_mfma_f32_32x32x16_bf16 v[48:63], v[88:91], v[156:159], v[48:63]
	v_mfma_f32_32x32x16_bf16 v[0:15], v[92:95], v[152:155], v[0:15]
	v_mfma_f32_32x32x16_bf16 v[16:31], v[92:95], v[156:159], v[16:31]
	v_mfma_f32_32x32x16_bf16 v[32:47], v[160:163], v[168:171], v[32:47]
	v_mfma_f32_32x32x16_bf16 v[48:63], v[160:163], v[172:175], v[48:63]
	v_mfma_f32_32x32x16_bf16 v[0:15], v[164:167], v[168:171], v[0:15]
	v_mfma_f32_32x32x16_bf16 v[16:31], v[164:167], v[172:175], v[16:31]
	ds_read_b128 v[88:91], v68
	ds_read_b128 v[92:95], v68 offset:2048
	ds_read_b128 v[152:155], v69 offset:8192
	ds_read_b128 v[156:159], v69 offset:10240
	ds_read_b128 v[160:163], v70
	ds_read_b128 v[164:167], v70 offset:2048
	ds_read_b128 v[168:171], v71 offset:8192
	ds_read_b128 v[172:175], v71 offset:10240
	s_mov_b64 s[68:69], 0xe000
	s_mov_b32 m0, s22
	s_mov_b64 s[64:65], 0xe400
	v_lshl_add_u64 v[182:183], v[64:65], 0, s[68:69]
	v_lshl_add_u64 v[180:181], v[64:65], 0, s[64:65]
	global_load_lds_dwordx4 v[182:183], off
	s_mov_b32 m0, s1
	v_lshl_add_u64 v[176:177], v[66:67], 0, s[68:69]
	global_load_lds_dwordx4 v[180:181], off
	s_mov_b32 m0, s21
	v_lshl_add_u64 v[178:179], v[66:67], 0, s[64:65]
	global_load_lds_dwordx4 v[176:177], off
	s_mov_b32 m0, s23
	s_nop 0
	global_load_lds_dwordx4 v[178:179], off
	s_waitcnt lgkmcnt(0)
	v_mfma_f32_32x32x16_bf16 v[32:47], v[88:91], v[152:155], v[32:47]
	s_waitcnt vmcnt(8)
	s_waitcnt lgkmcnt(0)
	s_barrier
	v_mfma_f32_32x32x16_bf16 v[48:63], v[88:91], v[156:159], v[48:63]
	v_mfma_f32_32x32x16_bf16 v[0:15], v[92:95], v[152:155], v[0:15]
	v_mfma_f32_32x32x16_bf16 v[16:31], v[92:95], v[156:159], v[16:31]
	v_mfma_f32_32x32x16_bf16 v[32:47], v[160:163], v[168:171], v[32:47]
	v_mfma_f32_32x32x16_bf16 v[48:63], v[160:163], v[172:175], v[48:63]
	v_mfma_f32_32x32x16_bf16 v[0:15], v[164:167], v[168:171], v[0:15]
	v_mfma_f32_32x32x16_bf16 v[16:31], v[164:167], v[172:175], v[16:31]
	ds_read_b128 v[88:91], v68 offset:16384
	ds_read_b128 v[92:95], v68 offset:18432
	ds_read_b128 v[152:155], v69 offset:24576
	ds_read_b128 v[156:159], v69 offset:26624
	ds_read_b128 v[160:163], v70 offset:16384
	ds_read_b128 v[164:167], v70 offset:18432
	ds_read_b128 v[168:171], v71 offset:24576
	ds_read_b128 v[172:175], v71 offset:26624
	s_mov_b64 s[68:69], 0x10000
	s_mov_b32 m0, s43
	s_mov_b64 s[64:65], 0x10400
	v_lshl_add_u64 v[182:183], v[64:65], 0, s[68:69]
	v_lshl_add_u64 v[180:181], v[64:65], 0, s[64:65]
	global_load_lds_dwordx4 v[182:183], off
	s_mov_b32 m0, s41
	v_lshl_add_u64 v[176:177], v[66:67], 0, s[68:69]
	global_load_lds_dwordx4 v[180:181], off
	s_mov_b32 m0, s42
	v_lshl_add_u64 v[178:179], v[66:67], 0, s[64:65]
	global_load_lds_dwordx4 v[176:177], off
	s_mov_b32 m0, s48
	s_nop 0
	global_load_lds_dwordx4 v[178:179], off
	s_waitcnt lgkmcnt(0)
	v_mfma_f32_32x32x16_bf16 v[32:47], v[88:91], v[152:155], v[32:47]
	s_waitcnt vmcnt(8)
	s_waitcnt lgkmcnt(0)
	s_barrier
	v_mfma_f32_32x32x16_bf16 v[48:63], v[88:91], v[156:159], v[48:63]
	v_mfma_f32_32x32x16_bf16 v[0:15], v[92:95], v[152:155], v[0:15]
	v_mfma_f32_32x32x16_bf16 v[16:31], v[92:95], v[156:159], v[16:31]
	v_mfma_f32_32x32x16_bf16 v[32:47], v[160:163], v[168:171], v[32:47]
	v_mfma_f32_32x32x16_bf16 v[48:63], v[160:163], v[172:175], v[48:63]
	v_mfma_f32_32x32x16_bf16 v[0:15], v[164:167], v[168:171], v[0:15]
	v_mfma_f32_32x32x16_bf16 v[16:31], v[164:167], v[172:175], v[16:31]
	ds_read_b128 v[88:91], v68 offset:32768
	ds_read_b128 v[92:95], v68 offset:34816
	ds_read_b128 v[152:155], v69 offset:40960
	ds_read_b128 v[156:159], v69 offset:43008
	ds_read_b128 v[160:163], v70 offset:32768
	ds_read_b128 v[164:167], v70 offset:34816
	ds_read_b128 v[168:171], v71 offset:40960
	ds_read_b128 v[172:175], v71 offset:43008
	s_mov_b64 s[68:69], 0x12000
	s_mov_b32 m0, s38
	s_mov_b64 s[64:65], 0x12400
	v_lshl_add_u64 v[182:183], v[64:65], 0, s[68:69]
	v_lshl_add_u64 v[180:181], v[64:65], 0, s[64:65]
	global_load_lds_dwordx4 v[182:183], off
	s_mov_b32 m0, s37
	v_lshl_add_u64 v[176:177], v[66:67], 0, s[68:69]
	global_load_lds_dwordx4 v[180:181], off
	s_mov_b32 m0, s39
	v_lshl_add_u64 v[178:179], v[66:67], 0, s[64:65]
	global_load_lds_dwordx4 v[176:177], off
	s_mov_b32 m0, s40
	s_nop 0
	global_load_lds_dwordx4 v[178:179], off
	s_waitcnt lgkmcnt(0)
	v_mfma_f32_32x32x16_bf16 v[32:47], v[88:91], v[152:155], v[32:47]
	s_waitcnt vmcnt(8)
	s_waitcnt lgkmcnt(0)
	s_barrier
	v_mfma_f32_32x32x16_bf16 v[48:63], v[88:91], v[156:159], v[48:63]
	v_mfma_f32_32x32x16_bf16 v[0:15], v[92:95], v[152:155], v[0:15]
	v_mfma_f32_32x32x16_bf16 v[16:31], v[92:95], v[156:159], v[16:31]
	v_mfma_f32_32x32x16_bf16 v[32:47], v[160:163], v[168:171], v[32:47]
	v_mfma_f32_32x32x16_bf16 v[48:63], v[160:163], v[172:175], v[48:63]
	v_mfma_f32_32x32x16_bf16 v[0:15], v[164:167], v[168:171], v[0:15]
	v_mfma_f32_32x32x16_bf16 v[16:31], v[164:167], v[172:175], v[16:31]
	ds_read_b128 v[88:91], v68 offset:49152
	ds_read_b128 v[92:95], v68 offset:51200
	ds_read_b128 v[152:155], v69 offset:57344
	ds_read_b128 v[156:159], v69 offset:59392
	ds_read_b128 v[160:163], v70 offset:49152
	ds_read_b128 v[164:167], v70 offset:51200
	ds_read_b128 v[168:171], v71 offset:57344
	ds_read_b128 v[172:175], v71 offset:59392
	s_mov_b64 s[68:69], 0x14000
	s_mov_b32 m0, s34
	s_mov_b64 s[64:65], 0x14400
	v_lshl_add_u64 v[182:183], v[64:65], 0, s[68:69]
	v_lshl_add_u64 v[180:181], v[64:65], 0, s[64:65]
	global_load_lds_dwordx4 v[182:183], off
	s_mov_b32 m0, s30
	v_lshl_add_u64 v[176:177], v[66:67], 0, s[68:69]
	global_load_lds_dwordx4 v[180:181], off
	s_mov_b32 m0, s35
	v_lshl_add_u64 v[178:179], v[66:67], 0, s[64:65]
	global_load_lds_dwordx4 v[176:177], off
	s_mov_b32 m0, s36
	s_nop 0
	global_load_lds_dwordx4 v[178:179], off
	s_waitcnt lgkmcnt(0)
	v_mfma_f32_32x32x16_bf16 v[32:47], v[88:91], v[152:155], v[32:47]
	s_waitcnt vmcnt(8)
	s_waitcnt lgkmcnt(0)
	s_barrier
	v_mfma_f32_32x32x16_bf16 v[48:63], v[88:91], v[156:159], v[48:63]
	v_mfma_f32_32x32x16_bf16 v[0:15], v[92:95], v[152:155], v[0:15]
	v_mfma_f32_32x32x16_bf16 v[16:31], v[92:95], v[156:159], v[16:31]
	v_mfma_f32_32x32x16_bf16 v[32:47], v[160:163], v[168:171], v[32:47]
	v_mfma_f32_32x32x16_bf16 v[48:63], v[160:163], v[172:175], v[48:63]
	v_mfma_f32_32x32x16_bf16 v[0:15], v[164:167], v[168:171], v[0:15]
	v_mfma_f32_32x32x16_bf16 v[16:31], v[164:167], v[172:175], v[16:31]
	ds_read_b128 v[88:91], v68
	ds_read_b128 v[92:95], v68 offset:2048
	ds_read_b128 v[152:155], v69 offset:8192
	ds_read_b128 v[156:159], v69 offset:10240
	ds_read_b128 v[160:163], v70
	ds_read_b128 v[164:167], v70 offset:2048
	ds_read_b128 v[168:171], v71 offset:8192
	ds_read_b128 v[172:175], v71 offset:10240
	s_mov_b64 s[68:69], 0x16000
	s_mov_b32 m0, s22
	s_mov_b64 s[64:65], 0x16400
	v_lshl_add_u64 v[182:183], v[64:65], 0, s[68:69]
	v_lshl_add_u64 v[180:181], v[64:65], 0, s[64:65]
	global_load_lds_dwordx4 v[182:183], off
	s_mov_b32 m0, s1
	v_lshl_add_u64 v[176:177], v[66:67], 0, s[68:69]
	global_load_lds_dwordx4 v[180:181], off
	s_mov_b32 m0, s21
	v_lshl_add_u64 v[178:179], v[66:67], 0, s[64:65]
	global_load_lds_dwordx4 v[176:177], off
	s_mov_b32 m0, s23
	s_nop 0
	global_load_lds_dwordx4 v[178:179], off
	s_waitcnt lgkmcnt(0)
	v_mfma_f32_32x32x16_bf16 v[32:47], v[88:91], v[152:155], v[32:47]
	s_waitcnt vmcnt(8)
	s_waitcnt lgkmcnt(0)
	s_barrier
	v_mfma_f32_32x32x16_bf16 v[48:63], v[88:91], v[156:159], v[48:63]
	v_mfma_f32_32x32x16_bf16 v[0:15], v[92:95], v[152:155], v[0:15]
	v_mfma_f32_32x32x16_bf16 v[16:31], v[92:95], v[156:159], v[16:31]
	v_mfma_f32_32x32x16_bf16 v[32:47], v[160:163], v[168:171], v[32:47]
	v_mfma_f32_32x32x16_bf16 v[48:63], v[160:163], v[172:175], v[48:63]
	v_mfma_f32_32x32x16_bf16 v[0:15], v[164:167], v[168:171], v[0:15]
	v_mfma_f32_32x32x16_bf16 v[16:31], v[164:167], v[172:175], v[16:31]
	ds_read_b128 v[88:91], v68 offset:16384
	ds_read_b128 v[92:95], v68 offset:18432
	ds_read_b128 v[152:155], v69 offset:24576
	ds_read_b128 v[156:159], v69 offset:26624
	ds_read_b128 v[160:163], v70 offset:16384
	ds_read_b128 v[164:167], v70 offset:18432
	ds_read_b128 v[168:171], v71 offset:24576
	ds_read_b128 v[172:175], v71 offset:26624
	s_mov_b64 s[68:69], 0x18000
	s_mov_b32 m0, s43
	s_mov_b64 s[64:65], 0x18400
	v_lshl_add_u64 v[182:183], v[64:65], 0, s[68:69]
	v_lshl_add_u64 v[180:181], v[64:65], 0, s[64:65]
	global_load_lds_dwordx4 v[182:183], off
	s_mov_b32 m0, s41
	v_lshl_add_u64 v[176:177], v[66:67], 0, s[68:69]
	global_load_lds_dwordx4 v[180:181], off
	s_mov_b32 m0, s42
	v_lshl_add_u64 v[178:179], v[66:67], 0, s[64:65]
	global_load_lds_dwordx4 v[176:177], off
	s_mov_b32 m0, s48
	s_nop 0
	global_load_lds_dwordx4 v[178:179], off
	s_waitcnt lgkmcnt(0)
	v_mfma_f32_32x32x16_bf16 v[32:47], v[88:91], v[152:155], v[32:47]
	s_waitcnt vmcnt(8)
	s_waitcnt lgkmcnt(0)
	s_barrier
	v_mfma_f32_32x32x16_bf16 v[48:63], v[88:91], v[156:159], v[48:63]
	v_mfma_f32_32x32x16_bf16 v[0:15], v[92:95], v[152:155], v[0:15]
	v_mfma_f32_32x32x16_bf16 v[16:31], v[92:95], v[156:159], v[16:31]
	v_mfma_f32_32x32x16_bf16 v[32:47], v[160:163], v[168:171], v[32:47]
	v_mfma_f32_32x32x16_bf16 v[48:63], v[160:163], v[172:175], v[48:63]
	v_mfma_f32_32x32x16_bf16 v[0:15], v[164:167], v[168:171], v[0:15]
	v_mfma_f32_32x32x16_bf16 v[16:31], v[164:167], v[172:175], v[16:31]
	ds_read_b128 v[88:91], v68 offset:32768
	ds_read_b128 v[92:95], v68 offset:34816
	ds_read_b128 v[152:155], v69 offset:40960
	ds_read_b128 v[156:159], v69 offset:43008
	ds_read_b128 v[160:163], v70 offset:32768
	ds_read_b128 v[164:167], v70 offset:34816
	ds_read_b128 v[168:171], v71 offset:40960
	ds_read_b128 v[172:175], v71 offset:43008
	s_mov_b64 s[48:49], 0x1a000
	s_mov_b32 m0, s38
	s_mov_b64 s[42:43], 0x1a400
	v_lshl_add_u64 v[182:183], v[64:65], 0, s[48:49]
	v_lshl_add_u64 v[180:181], v[64:65], 0, s[42:43]
	global_load_lds_dwordx4 v[182:183], off
	s_mov_b32 m0, s37
	v_lshl_add_u64 v[176:177], v[66:67], 0, s[48:49]
	global_load_lds_dwordx4 v[180:181], off
	s_mov_b32 m0, s39
	v_lshl_add_u64 v[178:179], v[66:67], 0, s[42:43]
	global_load_lds_dwordx4 v[176:177], off
	s_mov_b32 m0, s40
	s_nop 0
	global_load_lds_dwordx4 v[178:179], off
	s_waitcnt lgkmcnt(0)
	v_mfma_f32_32x32x16_bf16 v[32:47], v[88:91], v[152:155], v[32:47]
	s_waitcnt vmcnt(8)
	s_waitcnt lgkmcnt(0)
	s_barrier
	v_mfma_f32_32x32x16_bf16 v[48:63], v[88:91], v[156:159], v[48:63]
	v_mfma_f32_32x32x16_bf16 v[0:15], v[92:95], v[152:155], v[0:15]
	v_mfma_f32_32x32x16_bf16 v[16:31], v[92:95], v[156:159], v[16:31]
	v_mfma_f32_32x32x16_bf16 v[32:47], v[160:163], v[168:171], v[32:47]
	v_mfma_f32_32x32x16_bf16 v[48:63], v[160:163], v[172:175], v[48:63]
	v_mfma_f32_32x32x16_bf16 v[0:15], v[164:167], v[168:171], v[0:15]
	v_mfma_f32_32x32x16_bf16 v[16:31], v[164:167], v[172:175], v[16:31]
	ds_read_b128 v[88:91], v68 offset:49152
	ds_read_b128 v[92:95], v68 offset:51200
	ds_read_b128 v[152:155], v69 offset:57344
	ds_read_b128 v[156:159], v69 offset:59392
	ds_read_b128 v[160:163], v70 offset:49152
	ds_read_b128 v[164:167], v70 offset:51200
	ds_read_b128 v[168:171], v71 offset:57344
	ds_read_b128 v[172:175], v71 offset:59392
	s_mov_b64 s[40:41], 0x1c000
	s_mov_b32 m0, s34
	s_mov_b64 s[38:39], 0x1c400
	v_lshl_add_u64 v[182:183], v[64:65], 0, s[40:41]
	v_lshl_add_u64 v[180:181], v[64:65], 0, s[38:39]
	global_load_lds_dwordx4 v[182:183], off
	s_mov_b32 m0, s30
	v_lshl_add_u64 v[176:177], v[66:67], 0, s[40:41]
	global_load_lds_dwordx4 v[180:181], off
	s_mov_b32 m0, s35
	v_lshl_add_u64 v[178:179], v[66:67], 0, s[38:39]
	global_load_lds_dwordx4 v[176:177], off
	s_mov_b32 m0, s36
	s_nop 0
	global_load_lds_dwordx4 v[178:179], off
	s_waitcnt lgkmcnt(0)
	v_mfma_f32_32x32x16_bf16 v[32:47], v[88:91], v[152:155], v[32:47]
	s_waitcnt vmcnt(8)
	s_waitcnt lgkmcnt(0)
	s_barrier
	v_mfma_f32_32x32x16_bf16 v[48:63], v[88:91], v[156:159], v[48:63]
	v_mfma_f32_32x32x16_bf16 v[0:15], v[92:95], v[152:155], v[0:15]
	v_mfma_f32_32x32x16_bf16 v[16:31], v[92:95], v[156:159], v[16:31]
	v_mfma_f32_32x32x16_bf16 v[32:47], v[160:163], v[168:171], v[32:47]
	v_mfma_f32_32x32x16_bf16 v[48:63], v[160:163], v[172:175], v[48:63]
	v_mfma_f32_32x32x16_bf16 v[0:15], v[164:167], v[168:171], v[0:15]
	v_mfma_f32_32x32x16_bf16 v[16:31], v[164:167], v[172:175], v[16:31]
	ds_read_b128 v[88:91], v68
	ds_read_b128 v[92:95], v68 offset:2048
	ds_read_b128 v[152:155], v69 offset:8192
	ds_read_b128 v[156:159], v69 offset:10240
	ds_read_b128 v[160:163], v70
	ds_read_b128 v[164:167], v70 offset:2048
	ds_read_b128 v[168:171], v71 offset:8192
	ds_read_b128 v[172:175], v71 offset:10240
	s_mov_b64 s[36:37], 0x1e000
	s_mov_b32 m0, s22
	s_mov_b64 s[34:35], 0x1e400
	v_lshl_add_u64 v[182:183], v[64:65], 0, s[36:37]
	v_lshl_add_u64 v[180:181], v[64:65], 0, s[34:35]
	global_load_lds_dwordx4 v[182:183], off
	s_mov_b32 m0, s1
	v_lshl_add_u64 v[176:177], v[66:67], 0, s[36:37]
	global_load_lds_dwordx4 v[180:181], off
	s_mov_b32 m0, s21
	v_lshl_add_u64 v[178:179], v[66:67], 0, s[34:35]
	global_load_lds_dwordx4 v[176:177], off
	s_mov_b32 m0, s23
	s_nop 0
	global_load_lds_dwordx4 v[178:179], off
	s_waitcnt lgkmcnt(0)
	v_mfma_f32_32x32x16_bf16 v[32:47], v[88:91], v[152:155], v[32:47]
	s_waitcnt vmcnt(8)
	s_waitcnt lgkmcnt(0)
	s_barrier
	v_mfma_f32_32x32x16_bf16 v[48:63], v[88:91], v[156:159], v[48:63]
	v_mfma_f32_32x32x16_bf16 v[0:15], v[92:95], v[152:155], v[0:15]
	v_mfma_f32_32x32x16_bf16 v[16:31], v[92:95], v[156:159], v[16:31]
	v_mfma_f32_32x32x16_bf16 v[32:47], v[160:163], v[168:171], v[32:47]
	v_mfma_f32_32x32x16_bf16 v[48:63], v[160:163], v[172:175], v[48:63]
	v_mfma_f32_32x32x16_bf16 v[0:15], v[164:167], v[168:171], v[0:15]
	v_mfma_f32_32x32x16_bf16 v[16:31], v[164:167], v[172:175], v[16:31]
	ds_read_b128 v[88:91], v68 offset:16384
	ds_read_b128 v[92:95], v68 offset:18432
	ds_read_b128 v[152:155], v69 offset:24576
	ds_read_b128 v[156:159], v69 offset:26624
	ds_read_b128 v[160:163], v70 offset:16384
	ds_read_b128 v[164:167], v70 offset:18432
	ds_read_b128 v[168:171], v71 offset:24576
	ds_read_b128 v[172:175], v71 offset:26624
	s_mov_b64 s[34:35], 0x20000
	v_lshl_add_u64 v[176:177], v[66:67], 0, s[34:35]
	v_lshl_add_u64 v[182:183], v[64:65], 0, s[34:35]
	v_readfirstlane_b32 s34, v101
	s_mov_b64 s[22:23], 0x20400
	s_mov_b32 m0, s34
	v_readfirstlane_b32 s1, v84
	v_lshl_add_u64 v[180:181], v[64:65], 0, s[22:23]
	global_load_lds_dwordx4 v[182:183], off
	s_mov_b32 m0, s1
	v_readfirstlane_b32 s21, v85
	v_lshl_add_u64 v[178:179], v[66:67], 0, s[22:23]
	global_load_lds_dwordx4 v[180:181], off
	s_mov_b32 m0, s21
	v_readfirstlane_b32 s22, v86
	global_load_lds_dwordx4 v[176:177], off
	s_mov_b32 m0, s22
	s_nop 0
	global_load_lds_dwordx4 v[178:179], off
	s_waitcnt lgkmcnt(0)
	v_mfma_f32_32x32x16_bf16 v[32:47], v[88:91], v[152:155], v[32:47]
	s_waitcnt vmcnt(8)
	s_waitcnt lgkmcnt(0)
	s_barrier
	v_mfma_f32_32x32x16_bf16 v[48:63], v[88:91], v[156:159], v[48:63]
	v_mfma_f32_32x32x16_bf16 v[0:15], v[92:95], v[152:155], v[0:15]
	v_mfma_f32_32x32x16_bf16 v[16:31], v[92:95], v[156:159], v[16:31]
	v_mfma_f32_32x32x16_bf16 v[32:47], v[160:163], v[168:171], v[32:47]
	v_mfma_f32_32x32x16_bf16 v[48:63], v[160:163], v[172:175], v[48:63]
	v_mfma_f32_32x32x16_bf16 v[0:15], v[164:167], v[168:171], v[0:15]
	v_mfma_f32_32x32x16_bf16 v[16:31], v[164:167], v[172:175], v[16:31]
	ds_read_b128 v[84:87], v68 offset:32768
	ds_read_b128 v[88:91], v68 offset:34816
	ds_read_b128 v[92:95], v69 offset:40960
	ds_read_b128 v[152:155], v69 offset:43008
	ds_read_b128 v[156:159], v70 offset:32768
	ds_read_b128 v[160:163], v70 offset:34816
	ds_read_b128 v[164:167], v71 offset:40960
	ds_read_b128 v[168:171], v71 offset:43008
	s_mov_b64 s[38:39], 0x22000
	v_lshl_add_u64 v[172:173], v[66:67], 0, s[38:39]
	v_lshl_add_u64 v[178:179], v[64:65], 0, s[38:39]
	v_readfirstlane_b32 s38, v80
	s_mov_b64 s[36:37], 0x22400
	s_mov_b32 m0, s38
	v_readfirstlane_b32 s23, v81
	v_lshl_add_u64 v[176:177], v[64:65], 0, s[36:37]
	global_load_lds_dwordx4 v[178:179], off
	s_mov_b32 m0, s23
	v_readfirstlane_b32 s30, v82
	global_load_lds_dwordx4 v[176:177], off
	s_mov_b32 m0, s30
	v_readfirstlane_b32 s35, v83
	v_lshl_add_u64 v[174:175], v[66:67], 0, s[36:37]
	global_load_lds_dwordx4 v[172:173], off
	s_mov_b32 m0, s35
	s_nop 0
	global_load_lds_dwordx4 v[174:175], off
	s_waitcnt lgkmcnt(0)
	v_mfma_f32_32x32x16_bf16 v[32:47], v[84:87], v[92:95], v[32:47]
	s_waitcnt vmcnt(8)
	s_waitcnt lgkmcnt(0)
	s_barrier
	v_mfma_f32_32x32x16_bf16 v[48:63], v[84:87], v[152:155], v[48:63]
	v_mfma_f32_32x32x16_bf16 v[0:15], v[88:91], v[92:95], v[0:15]
	v_mfma_f32_32x32x16_bf16 v[16:31], v[88:91], v[152:155], v[16:31]
	v_mfma_f32_32x32x16_bf16 v[32:47], v[156:159], v[164:167], v[32:47]
	v_mfma_f32_32x32x16_bf16 v[48:63], v[156:159], v[168:171], v[48:63]
	v_mfma_f32_32x32x16_bf16 v[0:15], v[160:163], v[164:167], v[0:15]
	v_mfma_f32_32x32x16_bf16 v[16:31], v[160:163], v[168:171], v[16:31]
	ds_read_b128 v[80:83], v68 offset:49152
	ds_read_b128 v[84:87], v68 offset:51200
	ds_read_b128 v[88:91], v69 offset:57344
	ds_read_b128 v[92:95], v69 offset:59392
	ds_read_b128 v[152:155], v70 offset:49152
	ds_read_b128 v[156:159], v70 offset:51200
	ds_read_b128 v[160:163], v71 offset:57344
	ds_read_b128 v[164:167], v71 offset:59392
	s_mov_b64 s[40:41], 0x24000
	s_mov_b64 s[36:37], 0x24400
	v_readfirstlane_b32 s42, v76
	v_lshl_add_u64 v[170:171], v[66:67], 0, s[36:37]
	v_lshl_add_u64 v[172:173], v[64:65], 0, s[36:37]
	v_lshl_add_u64 v[174:175], v[64:65], 0, s[40:41]
	s_mov_b32 m0, s42
	v_readfirstlane_b32 s36, v77
	global_load_lds_dwordx4 v[174:175], off
	s_mov_b32 m0, s36
	v_readfirstlane_b32 s37, v78
	v_lshl_add_u64 v[168:169], v[66:67], 0, s[40:41]
	global_load_lds_dwordx4 v[172:173], off
	s_mov_b32 m0, s37
	v_readfirstlane_b32 s39, v79
	global_load_lds_dwordx4 v[168:169], off
	s_mov_b32 m0, s39
	s_nop 0
	global_load_lds_dwordx4 v[170:171], off
	s_waitcnt lgkmcnt(0)
	v_mfma_f32_32x32x16_bf16 v[32:47], v[80:83], v[88:91], v[32:47]
	s_waitcnt vmcnt(8)
	s_waitcnt lgkmcnt(0)
	s_barrier
	v_mfma_f32_32x32x16_bf16 v[48:63], v[80:83], v[92:95], v[48:63]
	v_mfma_f32_32x32x16_bf16 v[0:15], v[84:87], v[88:91], v[0:15]
	v_mfma_f32_32x32x16_bf16 v[16:31], v[84:87], v[92:95], v[16:31]
	v_mfma_f32_32x32x16_bf16 v[32:47], v[152:155], v[160:163], v[32:47]
	v_mfma_f32_32x32x16_bf16 v[48:63], v[152:155], v[164:167], v[48:63]
	v_mfma_f32_32x32x16_bf16 v[0:15], v[156:159], v[160:163], v[0:15]
	v_mfma_f32_32x32x16_bf16 v[16:31], v[156:159], v[164:167], v[16:31]
	ds_read_b128 v[76:79], v68
	ds_read_b128 v[80:83], v68 offset:2048
	ds_read_b128 v[84:87], v69 offset:8192
	ds_read_b128 v[88:91], v69 offset:10240
	ds_read_b128 v[92:95], v70
	ds_read_b128 v[152:155], v70 offset:2048
	ds_read_b128 v[156:159], v71 offset:8192
	ds_read_b128 v[160:163], v71 offset:10240
	s_mov_b64 s[48:49], 0x26000
	v_lshl_add_u64 v[164:165], v[66:67], 0, s[48:49]
	s_mov_b64 s[40:41], 0x26400
	v_lshl_add_u64 v[170:171], v[64:65], 0, s[48:49]
	v_readfirstlane_b32 s48, v72
	v_lshl_add_u64 v[166:167], v[66:67], 0, s[40:41]
	v_lshl_add_u64 v[168:169], v[64:65], 0, s[40:41]
	s_mov_b32 m0, s48
	v_readfirstlane_b32 s40, v73
	global_load_lds_dwordx4 v[170:171], off
	s_mov_b32 m0, s40
	v_readfirstlane_b32 s41, v74
	global_load_lds_dwordx4 v[168:169], off
	s_mov_b32 m0, s41
	v_readfirstlane_b32 s43, v75
	global_load_lds_dwordx4 v[164:165], off
	s_mov_b32 m0, s43
	s_nop 0
	global_load_lds_dwordx4 v[166:167], off
	s_waitcnt lgkmcnt(0)
	v_mfma_f32_32x32x16_bf16 v[32:47], v[76:79], v[84:87], v[32:47]
	s_waitcnt vmcnt(8)
	s_waitcnt lgkmcnt(0)
	s_barrier
	v_mfma_f32_32x32x16_bf16 v[48:63], v[76:79], v[88:91], v[48:63]
	v_mfma_f32_32x32x16_bf16 v[0:15], v[80:83], v[84:87], v[0:15]
	v_mfma_f32_32x32x16_bf16 v[16:31], v[80:83], v[88:91], v[16:31]
	v_mfma_f32_32x32x16_bf16 v[32:47], v[92:95], v[156:159], v[32:47]
	v_mfma_f32_32x32x16_bf16 v[48:63], v[92:95], v[160:163], v[48:63]
	v_mfma_f32_32x32x16_bf16 v[0:15], v[152:155], v[156:159], v[0:15]
	v_mfma_f32_32x32x16_bf16 v[16:31], v[152:155], v[160:163], v[16:31]
	ds_read_b128 v[72:75], v68 offset:16384
	ds_read_b128 v[76:79], v68 offset:18432
	ds_read_b128 v[80:83], v69 offset:24576
	ds_read_b128 v[84:87], v69 offset:26624
	ds_read_b128 v[88:91], v70 offset:16384
	ds_read_b128 v[92:95], v70 offset:18432
	ds_read_b128 v[152:155], v71 offset:24576
	ds_read_b128 v[156:159], v71 offset:26624
	s_mov_b64 s[64:65], 0x28000
	s_mov_b32 m0, s34
	s_mov_b64 s[68:69], 0x28400
	v_lshl_add_u64 v[166:167], v[64:65], 0, s[64:65]
	v_lshl_add_u64 v[164:165], v[64:65], 0, s[68:69]
	global_load_lds_dwordx4 v[166:167], off
	s_mov_b32 m0, s1
	v_lshl_add_u64 v[160:161], v[66:67], 0, s[64:65]
	global_load_lds_dwordx4 v[164:165], off
	s_mov_b32 m0, s21
	v_lshl_add_u64 v[162:163], v[66:67], 0, s[68:69]
	global_load_lds_dwordx4 v[160:161], off
	s_mov_b32 m0, s22
	s_nop 0
	global_load_lds_dwordx4 v[162:163], off
	s_waitcnt lgkmcnt(0)
	v_mfma_f32_32x32x16_bf16 v[32:47], v[72:75], v[80:83], v[32:47]
	s_waitcnt vmcnt(8)
	s_waitcnt lgkmcnt(0)
	s_barrier
	v_mfma_f32_32x32x16_bf16 v[48:63], v[72:75], v[84:87], v[48:63]
	v_mfma_f32_32x32x16_bf16 v[0:15], v[76:79], v[80:83], v[0:15]
	v_mfma_f32_32x32x16_bf16 v[16:31], v[76:79], v[84:87], v[16:31]
	v_mfma_f32_32x32x16_bf16 v[32:47], v[88:91], v[152:155], v[32:47]
	v_mfma_f32_32x32x16_bf16 v[48:63], v[88:91], v[156:159], v[48:63]
	v_mfma_f32_32x32x16_bf16 v[0:15], v[92:95], v[152:155], v[0:15]
	v_mfma_f32_32x32x16_bf16 v[16:31], v[92:95], v[156:159], v[16:31]
	ds_read_b128 v[72:75], v68 offset:32768
	ds_read_b128 v[76:79], v68 offset:34816
	ds_read_b128 v[80:83], v69 offset:40960
	ds_read_b128 v[84:87], v69 offset:43008
	ds_read_b128 v[88:91], v70 offset:32768
	ds_read_b128 v[92:95], v70 offset:34816
	ds_read_b128 v[152:155], v71 offset:40960
	ds_read_b128 v[156:159], v71 offset:43008
	s_mov_b64 s[64:65], 0x2a000
	s_mov_b32 m0, s38
	s_mov_b64 s[68:69], 0x2a400
	v_lshl_add_u64 v[166:167], v[64:65], 0, s[64:65]
	v_lshl_add_u64 v[164:165], v[64:65], 0, s[68:69]
	global_load_lds_dwordx4 v[166:167], off
	s_mov_b32 m0, s23
	v_lshl_add_u64 v[160:161], v[66:67], 0, s[64:65]
	global_load_lds_dwordx4 v[164:165], off
	s_mov_b32 m0, s30
	v_lshl_add_u64 v[162:163], v[66:67], 0, s[68:69]
	global_load_lds_dwordx4 v[160:161], off
	s_mov_b32 m0, s35
	s_nop 0
	global_load_lds_dwordx4 v[162:163], off
	s_waitcnt lgkmcnt(0)
	v_mfma_f32_32x32x16_bf16 v[32:47], v[72:75], v[80:83], v[32:47]
	s_waitcnt vmcnt(8)
	s_waitcnt lgkmcnt(0)
	s_barrier
	v_mfma_f32_32x32x16_bf16 v[48:63], v[72:75], v[84:87], v[48:63]
	v_mfma_f32_32x32x16_bf16 v[0:15], v[76:79], v[80:83], v[0:15]
	v_mfma_f32_32x32x16_bf16 v[16:31], v[76:79], v[84:87], v[16:31]
	v_mfma_f32_32x32x16_bf16 v[32:47], v[88:91], v[152:155], v[32:47]
	v_mfma_f32_32x32x16_bf16 v[48:63], v[88:91], v[156:159], v[48:63]
	v_mfma_f32_32x32x16_bf16 v[0:15], v[92:95], v[152:155], v[0:15]
	v_mfma_f32_32x32x16_bf16 v[16:31], v[92:95], v[156:159], v[16:31]
	ds_read_b128 v[72:75], v68 offset:49152
	ds_read_b128 v[76:79], v68 offset:51200
	ds_read_b128 v[80:83], v69 offset:57344
	ds_read_b128 v[84:87], v69 offset:59392
	ds_read_b128 v[88:91], v70 offset:49152
	ds_read_b128 v[92:95], v70 offset:51200
	ds_read_b128 v[152:155], v71 offset:57344
	ds_read_b128 v[156:159], v71 offset:59392
	s_mov_b64 s[64:65], 0x2c000
	s_mov_b32 m0, s42
	s_mov_b64 s[68:69], 0x2c400
	v_lshl_add_u64 v[166:167], v[64:65], 0, s[64:65]
	v_lshl_add_u64 v[164:165], v[64:65], 0, s[68:69]
	global_load_lds_dwordx4 v[166:167], off
	s_mov_b32 m0, s36
	v_lshl_add_u64 v[160:161], v[66:67], 0, s[64:65]
	global_load_lds_dwordx4 v[164:165], off
	s_mov_b32 m0, s37
	v_lshl_add_u64 v[162:163], v[66:67], 0, s[68:69]
	global_load_lds_dwordx4 v[160:161], off
	s_mov_b32 m0, s39
	s_nop 0
	global_load_lds_dwordx4 v[162:163], off
	s_waitcnt lgkmcnt(0)
	v_mfma_f32_32x32x16_bf16 v[32:47], v[72:75], v[80:83], v[32:47]
	s_waitcnt vmcnt(8)
	s_waitcnt lgkmcnt(0)
	s_barrier
	v_mfma_f32_32x32x16_bf16 v[48:63], v[72:75], v[84:87], v[48:63]
	v_mfma_f32_32x32x16_bf16 v[0:15], v[76:79], v[80:83], v[0:15]
	v_mfma_f32_32x32x16_bf16 v[16:31], v[76:79], v[84:87], v[16:31]
	v_mfma_f32_32x32x16_bf16 v[32:47], v[88:91], v[152:155], v[32:47]
	v_mfma_f32_32x32x16_bf16 v[48:63], v[88:91], v[156:159], v[48:63]
	v_mfma_f32_32x32x16_bf16 v[0:15], v[92:95], v[152:155], v[0:15]
	v_mfma_f32_32x32x16_bf16 v[16:31], v[92:95], v[156:159], v[16:31]
	ds_read_b128 v[72:75], v68
	ds_read_b128 v[76:79], v68 offset:2048
	ds_read_b128 v[80:83], v69 offset:8192
	ds_read_b128 v[84:87], v69 offset:10240
	ds_read_b128 v[88:91], v70
	ds_read_b128 v[92:95], v70 offset:2048
	ds_read_b128 v[152:155], v71 offset:8192
	ds_read_b128 v[156:159], v71 offset:10240
	s_mov_b64 s[64:65], 0x2e000
	s_mov_b32 m0, s48
	s_mov_b64 s[68:69], 0x2e400
	v_lshl_add_u64 v[166:167], v[64:65], 0, s[64:65]
	v_lshl_add_u64 v[164:165], v[64:65], 0, s[68:69]
	global_load_lds_dwordx4 v[166:167], off
	s_mov_b32 m0, s40
	v_lshl_add_u64 v[160:161], v[66:67], 0, s[64:65]
	global_load_lds_dwordx4 v[164:165], off
	s_mov_b32 m0, s41
	v_lshl_add_u64 v[162:163], v[66:67], 0, s[68:69]
	global_load_lds_dwordx4 v[160:161], off
	s_mov_b32 m0, s43
	s_nop 0
	global_load_lds_dwordx4 v[162:163], off
	s_waitcnt lgkmcnt(0)
	v_mfma_f32_32x32x16_bf16 v[32:47], v[72:75], v[80:83], v[32:47]
	s_waitcnt vmcnt(8)
	s_waitcnt lgkmcnt(0)
	s_barrier
	v_mfma_f32_32x32x16_bf16 v[48:63], v[72:75], v[84:87], v[48:63]
	v_mfma_f32_32x32x16_bf16 v[0:15], v[76:79], v[80:83], v[0:15]
	v_mfma_f32_32x32x16_bf16 v[16:31], v[76:79], v[84:87], v[16:31]
	v_mfma_f32_32x32x16_bf16 v[32:47], v[88:91], v[152:155], v[32:47]
	v_mfma_f32_32x32x16_bf16 v[48:63], v[88:91], v[156:159], v[48:63]
	v_mfma_f32_32x32x16_bf16 v[0:15], v[92:95], v[152:155], v[0:15]
	v_mfma_f32_32x32x16_bf16 v[16:31], v[92:95], v[156:159], v[16:31]
	ds_read_b128 v[72:75], v68 offset:16384
	ds_read_b128 v[76:79], v68 offset:18432
	ds_read_b128 v[80:83], v69 offset:24576
	ds_read_b128 v[84:87], v69 offset:26624
	ds_read_b128 v[88:91], v70 offset:16384
	ds_read_b128 v[92:95], v70 offset:18432
	ds_read_b128 v[152:155], v71 offset:24576
	ds_read_b128 v[156:159], v71 offset:26624
	s_mov_b64 s[64:65], 0x30000
	s_mov_b32 m0, s34
	s_mov_b64 s[68:69], 0x30400
	v_lshl_add_u64 v[166:167], v[64:65], 0, s[64:65]
	v_lshl_add_u64 v[164:165], v[64:65], 0, s[68:69]
	global_load_lds_dwordx4 v[166:167], off
	s_mov_b32 m0, s1
	v_lshl_add_u64 v[160:161], v[66:67], 0, s[64:65]
	global_load_lds_dwordx4 v[164:165], off
	s_mov_b32 m0, s21
	v_lshl_add_u64 v[162:163], v[66:67], 0, s[68:69]
	global_load_lds_dwordx4 v[160:161], off
	s_mov_b32 m0, s22
	s_nop 0
	global_load_lds_dwordx4 v[162:163], off
	s_waitcnt lgkmcnt(0)
	v_mfma_f32_32x32x16_bf16 v[32:47], v[72:75], v[80:83], v[32:47]
	s_waitcnt vmcnt(8)
	s_waitcnt lgkmcnt(0)
	s_barrier
	v_mfma_f32_32x32x16_bf16 v[48:63], v[72:75], v[84:87], v[48:63]
	v_mfma_f32_32x32x16_bf16 v[0:15], v[76:79], v[80:83], v[0:15]
	v_mfma_f32_32x32x16_bf16 v[16:31], v[76:79], v[84:87], v[16:31]
	v_mfma_f32_32x32x16_bf16 v[32:47], v[88:91], v[152:155], v[32:47]
	v_mfma_f32_32x32x16_bf16 v[48:63], v[88:91], v[156:159], v[48:63]
	v_mfma_f32_32x32x16_bf16 v[0:15], v[92:95], v[152:155], v[0:15]
	v_mfma_f32_32x32x16_bf16 v[16:31], v[92:95], v[156:159], v[16:31]
	ds_read_b128 v[72:75], v68 offset:32768
	ds_read_b128 v[76:79], v68 offset:34816
	ds_read_b128 v[80:83], v69 offset:40960
	ds_read_b128 v[84:87], v69 offset:43008
	ds_read_b128 v[88:91], v70 offset:32768
	ds_read_b128 v[92:95], v70 offset:34816
	ds_read_b128 v[152:155], v71 offset:40960
	ds_read_b128 v[156:159], v71 offset:43008
	s_mov_b64 s[64:65], 0x32000
	s_mov_b32 m0, s38
	s_mov_b64 s[68:69], 0x32400
	v_lshl_add_u64 v[166:167], v[64:65], 0, s[64:65]
	v_lshl_add_u64 v[164:165], v[64:65], 0, s[68:69]
	global_load_lds_dwordx4 v[166:167], off
	s_mov_b32 m0, s23
	v_lshl_add_u64 v[160:161], v[66:67], 0, s[64:65]
	global_load_lds_dwordx4 v[164:165], off
	s_mov_b32 m0, s30
	v_lshl_add_u64 v[162:163], v[66:67], 0, s[68:69]
	global_load_lds_dwordx4 v[160:161], off
	s_mov_b32 m0, s35
	s_nop 0
	global_load_lds_dwordx4 v[162:163], off
	s_waitcnt lgkmcnt(0)
	v_mfma_f32_32x32x16_bf16 v[32:47], v[72:75], v[80:83], v[32:47]
	s_waitcnt vmcnt(8)
	s_waitcnt lgkmcnt(0)
	s_barrier
	v_mfma_f32_32x32x16_bf16 v[48:63], v[72:75], v[84:87], v[48:63]
	v_mfma_f32_32x32x16_bf16 v[0:15], v[76:79], v[80:83], v[0:15]
	v_mfma_f32_32x32x16_bf16 v[16:31], v[76:79], v[84:87], v[16:31]
	v_mfma_f32_32x32x16_bf16 v[32:47], v[88:91], v[152:155], v[32:47]
	v_mfma_f32_32x32x16_bf16 v[48:63], v[88:91], v[156:159], v[48:63]
	v_mfma_f32_32x32x16_bf16 v[0:15], v[92:95], v[152:155], v[0:15]
	v_mfma_f32_32x32x16_bf16 v[16:31], v[92:95], v[156:159], v[16:31]
	ds_read_b128 v[72:75], v68 offset:49152
	ds_read_b128 v[76:79], v68 offset:51200
	ds_read_b128 v[80:83], v69 offset:57344
	ds_read_b128 v[84:87], v69 offset:59392
	ds_read_b128 v[88:91], v70 offset:49152
	ds_read_b128 v[92:95], v70 offset:51200
	ds_read_b128 v[152:155], v71 offset:57344
	ds_read_b128 v[156:159], v71 offset:59392
	s_mov_b64 s[64:65], 0x34000
	s_mov_b32 m0, s42
	s_mov_b64 s[68:69], 0x34400
	v_lshl_add_u64 v[166:167], v[64:65], 0, s[64:65]
	v_lshl_add_u64 v[164:165], v[64:65], 0, s[68:69]
	global_load_lds_dwordx4 v[166:167], off
	s_mov_b32 m0, s36
	v_lshl_add_u64 v[160:161], v[66:67], 0, s[64:65]
	global_load_lds_dwordx4 v[164:165], off
	s_mov_b32 m0, s37
	v_lshl_add_u64 v[162:163], v[66:67], 0, s[68:69]
	global_load_lds_dwordx4 v[160:161], off
	s_mov_b32 m0, s39
	s_nop 0
	global_load_lds_dwordx4 v[162:163], off
	s_waitcnt lgkmcnt(0)
	v_mfma_f32_32x32x16_bf16 v[32:47], v[72:75], v[80:83], v[32:47]
	s_waitcnt vmcnt(8)
	s_waitcnt lgkmcnt(0)
	s_barrier
	v_mfma_f32_32x32x16_bf16 v[48:63], v[72:75], v[84:87], v[48:63]
	v_mfma_f32_32x32x16_bf16 v[0:15], v[76:79], v[80:83], v[0:15]
	v_mfma_f32_32x32x16_bf16 v[16:31], v[76:79], v[84:87], v[16:31]
	v_mfma_f32_32x32x16_bf16 v[32:47], v[88:91], v[152:155], v[32:47]
	v_mfma_f32_32x32x16_bf16 v[48:63], v[88:91], v[156:159], v[48:63]
	v_mfma_f32_32x32x16_bf16 v[0:15], v[92:95], v[152:155], v[0:15]
	v_mfma_f32_32x32x16_bf16 v[16:31], v[92:95], v[156:159], v[16:31]
	ds_read_b128 v[72:75], v68
	ds_read_b128 v[76:79], v68 offset:2048
	ds_read_b128 v[80:83], v69 offset:8192
	ds_read_b128 v[84:87], v69 offset:10240
	ds_read_b128 v[88:91], v70
	ds_read_b128 v[92:95], v70 offset:2048
	ds_read_b128 v[152:155], v71 offset:8192
	ds_read_b128 v[156:159], v71 offset:10240
	s_mov_b64 s[64:65], 0x36000
	s_mov_b32 m0, s48
	s_mov_b64 s[68:69], 0x36400
	v_lshl_add_u64 v[166:167], v[64:65], 0, s[64:65]
	v_lshl_add_u64 v[164:165], v[64:65], 0, s[68:69]
	global_load_lds_dwordx4 v[166:167], off
	s_mov_b32 m0, s40
	v_lshl_add_u64 v[160:161], v[66:67], 0, s[64:65]
	global_load_lds_dwordx4 v[164:165], off
	s_mov_b32 m0, s41
	v_lshl_add_u64 v[162:163], v[66:67], 0, s[68:69]
	global_load_lds_dwordx4 v[160:161], off
	s_mov_b32 m0, s43
	s_nop 0
	global_load_lds_dwordx4 v[162:163], off
	s_waitcnt lgkmcnt(0)
	v_mfma_f32_32x32x16_bf16 v[32:47], v[72:75], v[80:83], v[32:47]
	s_waitcnt vmcnt(8)
	s_waitcnt lgkmcnt(0)
	s_barrier
	v_mfma_f32_32x32x16_bf16 v[48:63], v[72:75], v[84:87], v[48:63]
	v_mfma_f32_32x32x16_bf16 v[0:15], v[76:79], v[80:83], v[0:15]
	v_mfma_f32_32x32x16_bf16 v[16:31], v[76:79], v[84:87], v[16:31]
	v_mfma_f32_32x32x16_bf16 v[32:47], v[88:91], v[152:155], v[32:47]
	v_mfma_f32_32x32x16_bf16 v[48:63], v[88:91], v[156:159], v[48:63]
	v_mfma_f32_32x32x16_bf16 v[0:15], v[92:95], v[152:155], v[0:15]
	v_mfma_f32_32x32x16_bf16 v[16:31], v[92:95], v[156:159], v[16:31]
	ds_read_b128 v[72:75], v68 offset:16384
	ds_read_b128 v[76:79], v68 offset:18432
	ds_read_b128 v[80:83], v69 offset:24576
	ds_read_b128 v[84:87], v69 offset:26624
	ds_read_b128 v[88:91], v70 offset:16384
	ds_read_b128 v[92:95], v70 offset:18432
	ds_read_b128 v[152:155], v71 offset:24576
	ds_read_b128 v[156:159], v71 offset:26624
	s_mov_b64 s[64:65], 0x38000
	s_mov_b32 m0, s34
	s_mov_b64 s[68:69], 0x38400
	v_lshl_add_u64 v[166:167], v[64:65], 0, s[64:65]
	v_lshl_add_u64 v[164:165], v[64:65], 0, s[68:69]
	global_load_lds_dwordx4 v[166:167], off
	s_mov_b32 m0, s1
	v_lshl_add_u64 v[160:161], v[66:67], 0, s[64:65]
	global_load_lds_dwordx4 v[164:165], off
	s_mov_b32 m0, s21
	v_lshl_add_u64 v[162:163], v[66:67], 0, s[68:69]
	global_load_lds_dwordx4 v[160:161], off
	s_mov_b32 m0, s22
	s_nop 0
	global_load_lds_dwordx4 v[162:163], off
	s_waitcnt lgkmcnt(0)
	v_mfma_f32_32x32x16_bf16 v[32:47], v[72:75], v[80:83], v[32:47]
	s_waitcnt vmcnt(8)
	s_waitcnt lgkmcnt(0)
	s_barrier
	v_mfma_f32_32x32x16_bf16 v[48:63], v[72:75], v[84:87], v[48:63]
	v_mfma_f32_32x32x16_bf16 v[0:15], v[76:79], v[80:83], v[0:15]
	v_mfma_f32_32x32x16_bf16 v[16:31], v[76:79], v[84:87], v[16:31]
	v_mfma_f32_32x32x16_bf16 v[32:47], v[88:91], v[152:155], v[32:47]
	v_mfma_f32_32x32x16_bf16 v[48:63], v[88:91], v[156:159], v[48:63]
	v_mfma_f32_32x32x16_bf16 v[0:15], v[92:95], v[152:155], v[0:15]
	v_mfma_f32_32x32x16_bf16 v[16:31], v[92:95], v[156:159], v[16:31]
	ds_read_b128 v[72:75], v68 offset:32768
	ds_read_b128 v[76:79], v68 offset:34816
	ds_read_b128 v[80:83], v69 offset:40960
	ds_read_b128 v[84:87], v69 offset:43008
	ds_read_b128 v[88:91], v70 offset:32768
	ds_read_b128 v[92:95], v70 offset:34816
	ds_read_b128 v[152:155], v71 offset:40960
	ds_read_b128 v[156:159], v71 offset:43008
	s_mov_b64 s[64:65], 0x3a000
	s_mov_b32 m0, s38
	s_mov_b64 s[68:69], 0x3a400
	v_lshl_add_u64 v[166:167], v[64:65], 0, s[64:65]
	v_lshl_add_u64 v[164:165], v[64:65], 0, s[68:69]
	global_load_lds_dwordx4 v[166:167], off
	s_mov_b32 m0, s23
	v_lshl_add_u64 v[160:161], v[66:67], 0, s[64:65]
	global_load_lds_dwordx4 v[164:165], off
	s_mov_b32 m0, s30
	v_lshl_add_u64 v[162:163], v[66:67], 0, s[68:69]
	global_load_lds_dwordx4 v[160:161], off
	s_mov_b32 m0, s35
	s_nop 0
	global_load_lds_dwordx4 v[162:163], off
	s_waitcnt lgkmcnt(0)
	v_mfma_f32_32x32x16_bf16 v[32:47], v[72:75], v[80:83], v[32:47]
	s_waitcnt vmcnt(8)
	s_waitcnt lgkmcnt(0)
	s_barrier
	v_mfma_f32_32x32x16_bf16 v[48:63], v[72:75], v[84:87], v[48:63]
	v_mfma_f32_32x32x16_bf16 v[0:15], v[76:79], v[80:83], v[0:15]
	v_mfma_f32_32x32x16_bf16 v[16:31], v[76:79], v[84:87], v[16:31]
	v_mfma_f32_32x32x16_bf16 v[32:47], v[88:91], v[152:155], v[32:47]
	v_mfma_f32_32x32x16_bf16 v[48:63], v[88:91], v[156:159], v[48:63]
	v_mfma_f32_32x32x16_bf16 v[0:15], v[92:95], v[152:155], v[0:15]
	v_mfma_f32_32x32x16_bf16 v[16:31], v[92:95], v[156:159], v[16:31]
	ds_read_b128 v[72:75], v68 offset:49152
	ds_read_b128 v[76:79], v68 offset:51200
	ds_read_b128 v[80:83], v69 offset:57344
	ds_read_b128 v[84:87], v69 offset:59392
	ds_read_b128 v[88:91], v70 offset:49152
	ds_read_b128 v[92:95], v70 offset:51200
	ds_read_b128 v[152:155], v71 offset:57344
	ds_read_b128 v[156:159], v71 offset:59392
	s_mov_b64 s[22:23], 0x3c000
	s_mov_b32 m0, s42
	s_mov_b64 s[34:35], 0x3c400
	v_lshl_add_u64 v[166:167], v[64:65], 0, s[22:23]
	v_lshl_add_u64 v[164:165], v[64:65], 0, s[34:35]
	global_load_lds_dwordx4 v[166:167], off
	s_mov_b32 m0, s36
	v_lshl_add_u64 v[160:161], v[66:67], 0, s[22:23]
	global_load_lds_dwordx4 v[164:165], off
	s_mov_b32 m0, s37
	v_lshl_add_u64 v[162:163], v[66:67], 0, s[34:35]
	global_load_lds_dwordx4 v[160:161], off
	s_mov_b32 m0, s39
	s_nop 0
	global_load_lds_dwordx4 v[162:163], off
	s_waitcnt lgkmcnt(0)
	v_mfma_f32_32x32x16_bf16 v[32:47], v[72:75], v[80:83], v[32:47]
	s_waitcnt vmcnt(8)
	s_waitcnt lgkmcnt(0)
	s_barrier
	v_mfma_f32_32x32x16_bf16 v[48:63], v[72:75], v[84:87], v[48:63]
	v_mfma_f32_32x32x16_bf16 v[0:15], v[76:79], v[80:83], v[0:15]
	v_mfma_f32_32x32x16_bf16 v[16:31], v[76:79], v[84:87], v[16:31]
	v_mfma_f32_32x32x16_bf16 v[32:47], v[88:91], v[152:155], v[32:47]
	v_mfma_f32_32x32x16_bf16 v[48:63], v[88:91], v[156:159], v[48:63]
	v_mfma_f32_32x32x16_bf16 v[0:15], v[92:95], v[152:155], v[0:15]
	v_mfma_f32_32x32x16_bf16 v[16:31], v[92:95], v[156:159], v[16:31]
	ds_read_b128 v[72:75], v68
	ds_read_b128 v[76:79], v68 offset:2048
	ds_read_b128 v[80:83], v69 offset:8192
	ds_read_b128 v[84:87], v69 offset:10240
	ds_read_b128 v[88:91], v70
	ds_read_b128 v[92:95], v70 offset:2048
	ds_read_b128 v[152:155], v71 offset:8192
	ds_read_b128 v[156:159], v71 offset:10240
	s_mov_b64 s[22:23], 0x3e000
	s_mov_b64 s[34:35], 0x3e400
	s_mov_b32 m0, s48
	v_lshl_add_u64 v[162:163], v[64:65], 0, s[34:35]
	v_lshl_add_u64 v[64:65], v[64:65], 0, s[22:23]
	global_load_lds_dwordx4 v[64:65], off
	s_mov_b32 m0, s40
	v_lshl_add_u64 v[160:161], v[66:67], 0, s[22:23]
	global_load_lds_dwordx4 v[162:163], off
	s_mov_b32 m0, s41
	v_lshl_add_u64 v[66:67], v[66:67], 0, s[34:35]
	global_load_lds_dwordx4 v[160:161], off
	s_mov_b32 m0, s43
	s_nop 0
	global_load_lds_dwordx4 v[66:67], off
	s_waitcnt lgkmcnt(0)
	v_mfma_f32_32x32x16_bf16 v[32:47], v[72:75], v[80:83], v[32:47]
	s_waitcnt vmcnt(8)
	s_waitcnt lgkmcnt(0)
	s_barrier
	v_mfma_f32_32x32x16_bf16 v[48:63], v[72:75], v[84:87], v[48:63]
	v_mfma_f32_32x32x16_bf16 v[0:15], v[76:79], v[80:83], v[0:15]
	v_mfma_f32_32x32x16_bf16 v[16:31], v[76:79], v[84:87], v[16:31]
	v_mfma_f32_32x32x16_bf16 v[32:47], v[88:91], v[152:155], v[32:47]
	v_mfma_f32_32x32x16_bf16 v[48:63], v[88:91], v[156:159], v[48:63]
	v_mfma_f32_32x32x16_bf16 v[0:15], v[92:95], v[152:155], v[0:15]
	v_mfma_f32_32x32x16_bf16 v[16:31], v[92:95], v[156:159], v[16:31]
	ds_read_b128 v[64:67], v68 offset:16384
	ds_read_b128 v[72:75], v68 offset:18432
	ds_read_b128 v[76:79], v69 offset:24576
	ds_read_b128 v[80:83], v69 offset:26624
	ds_read_b128 v[84:87], v70 offset:16384
	ds_read_b128 v[88:91], v70 offset:18432
	ds_read_b128 v[92:95], v71 offset:24576
	ds_read_b128 v[152:155], v71 offset:26624
	s_waitcnt lgkmcnt(0)
	v_mfma_f32_32x32x16_bf16 v[32:47], v[64:67], v[76:79], v[32:47]
	s_waitcnt vmcnt(4)
	s_waitcnt lgkmcnt(0)
	s_barrier
	v_mfma_f32_32x32x16_bf16 v[48:63], v[64:67], v[80:83], v[48:63]
	v_mfma_f32_32x32x16_bf16 v[0:15], v[72:75], v[76:79], v[0:15]
	v_mfma_f32_32x32x16_bf16 v[16:31], v[72:75], v[80:83], v[16:31]
	v_mfma_f32_32x32x16_bf16 v[32:47], v[84:87], v[92:95], v[32:47]
	v_mfma_f32_32x32x16_bf16 v[48:63], v[84:87], v[152:155], v[48:63]
	v_mfma_f32_32x32x16_bf16 v[0:15], v[88:91], v[92:95], v[0:15]
	v_mfma_f32_32x32x16_bf16 v[16:31], v[88:91], v[152:155], v[16:31]
	ds_read_b128 v[64:67], v68 offset:32768
	ds_read_b128 v[72:75], v68 offset:34816
	ds_read_b128 v[76:79], v69 offset:40960
	ds_read_b128 v[80:83], v69 offset:43008
	ds_read_b128 v[84:87], v70 offset:32768
	ds_read_b128 v[88:91], v70 offset:34816
	ds_read_b128 v[92:95], v71 offset:40960
	ds_read_b128 v[152:155], v71 offset:43008
	s_waitcnt lgkmcnt(0)
	v_mfma_f32_32x32x16_bf16 v[32:47], v[64:67], v[76:79], v[32:47]
	s_waitcnt vmcnt(0)
	s_waitcnt lgkmcnt(0)
	s_barrier
	v_mfma_f32_32x32x16_bf16 v[48:63], v[64:67], v[80:83], v[48:63]
	v_mfma_f32_32x32x16_bf16 v[0:15], v[72:75], v[76:79], v[0:15]
	v_mfma_f32_32x32x16_bf16 v[16:31], v[72:75], v[80:83], v[16:31]
	v_mfma_f32_32x32x16_bf16 v[32:47], v[84:87], v[92:95], v[32:47]
	v_mfma_f32_32x32x16_bf16 v[48:63], v[84:87], v[152:155], v[48:63]
	v_mfma_f32_32x32x16_bf16 v[0:15], v[88:91], v[92:95], v[0:15]
	v_mfma_f32_32x32x16_bf16 v[16:31], v[88:91], v[152:155], v[16:31]
	ds_read_b128 v[64:67], v68 offset:49152
	ds_read_b128 v[72:75], v68 offset:51200
	ds_read_b128 v[76:79], v69 offset:57344
	ds_read_b128 v[80:83], v69 offset:59392
	ds_read_b128 v[84:87], v70 offset:49152
	ds_read_b128 v[88:91], v70 offset:51200
	ds_read_b128 v[92:95], v71 offset:57344
	ds_read_b128 v[68:71], v71 offset:59392
	s_lshl_b32 s21, s0, 7
	s_add_i32 s1, s21, 0xfffff000
	s_lshr_b32 s1, s1, 10
	s_add_i32 s1, s1, 1
	s_cmp_gt_i32 s0, 31
	s_cselect_b32 s0, s1, 0
	s_mul_i32 s1, s12, 3
	s_add_i32 s0, s0, s1
	s_waitcnt lgkmcnt(0)
	v_mfma_f32_32x32x16_bf16 v[48:63], v[64:67], v[80:83], v[48:63]
	s_mul_hi_u32 s1, s0, 0x6000
	s_mulk_i32 s0, 0x6000
	s_add_u32 s22, s16, s0
	s_addc_u32 s23, s17, s1
	s_movk_i32 s0, 0x2000
	s_lshl_b32 s30, s20, 2
	s_waitcnt lgkmcnt(0)
	v_mfma_f32_32x32x16_bf16 v[16:31], v[72:75], v[80:83], v[16:31]
	s_barrier
	v_add_u32_e32 v186, s21, v191
	v_ashrrev_i32_e32 v187, 31, v186
	v_lshl_add_u64 v[156:157], v[102:103], 0, s[30:31]
	v_lshlrev_b64 v[188:189], 12, v[186:187]
	v_add_u32_e32 v182, s21, v192
	v_ashrrev_i32_e32 v183, 31, v182
	v_mfma_f32_32x32x16_bf16 v[32:47], v[64:67], v[76:79], v[32:47]
	v_or_b32_e32 v64, s20, v190
	v_lshlrev_b32_e32 v64, 2, v64
	v_mov_b32_e32 v65, v117
	v_lshl_add_u64 v[64:65], s[22:23], 0, v[64:65]
	v_lshl_add_u64 v[66:67], v[64:65], 0, s[44:45]
	v_add_co_u32_e64 v64, s[0:1], s0, v64
	v_mfma_f32_32x32x16_bf16 v[48:63], v[84:87], v[68:71], v[48:63]
	s_nop 0
	v_addc_co_u32_e64 v65, s[0:1], 0, v65, s[0:1]
	s_add_u32 s0, s22, s30
	s_addc_u32 s1, s23, 0
	global_load_dword v137, v[64:65], off
	global_load_dword v139, v[66:67], off offset:128
	v_lshl_add_u64 v[64:65], v[104:105], 0, s[30:31]
	global_load_dwordx4 v[64:67], v[64:65], off
	v_mfma_f32_32x32x16_bf16 v[16:31], v[88:91], v[68:71], v[16:31]
	v_lshl_add_u64 v[68:69], s[0:1], 0, v[116:117]
	s_movk_i32 s0, 0x4000
	v_add_co_u32_e64 v68, s[0:1], s0, v68
	v_add_u32_e32 v178, s21, v193
	s_nop 0
	v_addc_co_u32_e64 v69, s[0:1], 0, v69, s[0:1]
	global_load_dwordx4 v[68:71], v[68:69], off
	v_mfma_f32_32x32x16_bf16 v[0:15], v[72:75], v[76:79], v[0:15]
	v_lshlrev_b64 v[184:185], 12, v[182:183]
	v_ashrrev_i32_e32 v179, 31, v178
	v_add_u32_e32 v174, s21, v194
	v_lshlrev_b64 v[180:181], 12, v[178:179]
	v_ashrrev_i32_e32 v175, 31, v174
	v_add_u32_e32 v170, s21, v195
	v_lshlrev_b64 v[176:177], 12, v[174:175]
	v_mfma_f32_32x32x16_bf16 v[32:47], v[84:87], v[92:95], v[32:47]
	v_ashrrev_i32_e32 v171, 31, v170
	v_add_u32_e32 v166, s21, v196
	v_lshlrev_b64 v[172:173], 12, v[170:171]
	v_ashrrev_i32_e32 v167, 31, v166
	v_add_u32_e32 v162, s21, v197
	v_lshlrev_b64 v[168:169], 12, v[166:167]
	v_ashrrev_i32_e32 v163, 31, v162
	v_mfma_f32_32x32x16_bf16 v[0:15], v[88:91], v[92:95], v[0:15]
	v_add_u32_e32 v158, s21, v198
	v_lshlrev_b64 v[164:165], 12, v[162:163]
	v_ashrrev_i32_e32 v159, 31, v158
	v_lshlrev_b64 v[160:161], 12, v[158:159]
	v_add_u32_e32 v141, 0x400, v199
	v_add_u32_e32 v143, 0x1000, v199
	v_add_u32_e32 v145, 0x1400, v199
	v_add_u32_e32 v147, 0x2000, v199
	v_add_u32_e32 v149, 0x2400, v199
	v_add_u32_e32 v151, 0x3000, v199
	v_add_u32_e32 v209, 0x3200, v199
	v_add_u32_e32 v210, 0x3400, v199
	v_add_u32_e32 v211, 0x3600, v199
	v_mov_b32_e32 v107, v117
	v_mov_b32_e32 v109, v117
	s_waitcnt vmcnt(0)
	v_mul_f32_e32 v32, v32, v137
	v_mul_f32_e32 v48, v48, v139
	ds_write2_b32 v199, v32, v48 offset1:32
	v_mul_f32_e32 v32, v33, v137
	v_mul_f32_e32 v33, v49, v139
	ds_write2_b32 v199, v32, v33 offset0:132 offset1:164
	v_mul_f32_e32 v32, v34, v137
	v_mul_f32_e32 v33, v50, v139
	ds_write2_b32 v141, v32, v33 offset0:8 offset1:40
	v_mul_f32_e32 v32, v35, v137
	v_mul_f32_e32 v33, v51, v139
	ds_write2_b32 v141, v32, v33 offset0:140 offset1:172
	v_pk_add_f32 v[68:69], v[68:69], 1.0 op_sel_hi:[1,0]
	v_pk_add_f32 v[70:71], v[70:71], 1.0 op_sel_hi:[1,0]
	v_pk_mul_f32 v[152:153], v[64:65], v[68:69]
	v_lshl_add_u64 v[64:65], v[156:157], 0, v[188:189]
	global_load_dwordx4 v[92:95], v[64:65], off
	v_lshl_add_u64 v[64:65], v[156:157], 0, v[184:185]
	global_load_dwordx4 v[88:91], v[64:65], off
	v_lshl_add_u64 v[64:65], v[156:157], 0, v[180:181]
	global_load_dwordx4 v[84:87], v[64:65], off
	v_lshl_add_u64 v[64:65], v[156:157], 0, v[176:177]
	global_load_dwordx4 v[80:83], v[64:65], off
	v_lshl_add_u64 v[64:65], v[156:157], 0, v[172:173]
	global_load_dwordx4 v[76:79], v[64:65], off
	v_lshl_add_u64 v[64:65], v[156:157], 0, v[168:169]
	global_load_dwordx4 v[72:75], v[64:65], off
	v_lshl_add_u64 v[64:65], v[156:157], 0, v[164:165]
	v_pk_mul_f32 v[154:155], v[66:67], v[70:71]
	global_load_dwordx4 v[68:71], v[64:65], off
	v_lshl_add_u64 v[64:65], v[156:157], 0, v[160:161]
	global_load_dwordx4 v[64:67], v[64:65], off
	v_mul_f32_e32 v32, v36, v137
	v_mul_f32_e32 v33, v52, v139
	ds_write2_b32 v143, v32, v33 offset0:32 offset1:64
	v_mul_f32_e32 v32, v37, v137
	v_mul_f32_e32 v33, v53, v139
	ds_write2_b32 v143, v32, v33 offset0:164 offset1:196
	v_mul_f32_e32 v32, v38, v137
	v_mul_f32_e32 v33, v54, v139
	ds_write2_b32 v145, v32, v33 offset0:40 offset1:72
	v_mul_f32_e32 v32, v39, v137
	v_mul_f32_e32 v33, v55, v139
	ds_write2_b32 v145, v32, v33 offset0:172 offset1:204
	v_mul_f32_e32 v32, v40, v137
	v_mul_f32_e32 v33, v56, v139
	ds_write2_b32 v147, v32, v33 offset0:64 offset1:96
	v_mul_f32_e32 v32, v41, v137
	v_mul_f32_e32 v33, v57, v139
	ds_write2_b32 v147, v32, v33 offset0:196 offset1:228
	v_mul_f32_e32 v32, v42, v137
	v_mul_f32_e32 v33, v58, v139
	ds_write2_b32 v149, v32, v33 offset0:72 offset1:104
	v_mul_f32_e32 v32, v43, v137
	v_mul_f32_e32 v33, v59, v139
	ds_write2_b32 v149, v32, v33 offset0:204 offset1:236
	v_mul_f32_e32 v32, v44, v137
	v_mul_f32_e32 v33, v60, v139
	ds_write2_b32 v151, v32, v33 offset0:96 offset1:128
	v_mul_f32_e32 v32, v45, v137
	v_mul_f32_e32 v33, v61, v139
	ds_write2_b32 v209, v32, v33 offset0:100 offset1:132
	v_mul_f32_e32 v32, v46, v137
	v_mul_f32_e32 v33, v62, v139
	ds_write2_b32 v210, v32, v33 offset0:104 offset1:136
	v_mul_f32_e32 v32, v47, v137
	v_mul_f32_e32 v33, v63, v139
	ds_write2_b32 v211, v32, v33 offset0:108 offset1:140
	s_waitcnt lgkmcnt(0)
	s_barrier
	ds_read_b128 v[32:35], v208
	v_lshl_add_u64 v[36:37], s[46:47], 0, v[188:189]
	v_lshl_add_u64 v[36:37], v[36:37], 0, s[30:31]
	v_lshl_add_u64 v[36:37], v[36:37], 0, v[116:117]
	v_or_b32_e32 v40, s20, v100
	v_lshlrev_b32_e32 v40, 8, v40
	v_and_b32_e32 v60, 0x3e000, v40
	v_mov_b32_e32 v61, v117
	s_waitcnt vmcnt(7) lgkmcnt(0)
	v_pk_add_f32 v[34:35], v[94:95], v[34:35]
	v_pk_add_f32 v[32:33], v[92:93], v[32:33]
	global_store_dwordx4 v[36:37], v[32:35], off
	v_pk_mul_f32 v[38:39], v[152:153], v[32:33]
	v_pk_mul_f32 v[36:37], v[154:155], v[34:35]
	v_mul_f32_e32 v33, v33, v33
	v_fmac_f32_e32 v33, v32, v32
	v_and_b32_e32 v32, 64, v213
	v_fmac_f32_e32 v33, v34, v34
	v_add_u32_e32 v34, 64, v32
	v_xor_b32_e32 v32, 16, v213
	v_cmp_lt_i32_e64 s[0:1], v32, v34
	v_fmac_f32_e32 v33, v35, v35
	v_cvt_pk_bf16_f32 v38, v38, v39
	v_cndmask_b32_e64 v32, v213, v32, s[0:1]
	v_lshlrev_b32_e32 v92, 2, v32
	ds_bpermute_b32 v32, v92, v33
	v_cvt_pk_bf16_f32 v39, v36, v37
	v_ashrrev_i32_e32 v36, 7, v186
	v_ashrrev_i32_e32 v37, 31, v36
	v_lshlrev_b64 v[36:37], 18, v[36:37]
	s_waitcnt lgkmcnt(0)
	v_add_f32_e32 v32, v33, v32
	v_xor_b32_e32 v33, 8, v213
	v_cmp_lt_i32_e64 s[0:1], v33, v34
	v_lshl_add_u64 v[36:37], s[10:11], 0, v[36:37]
	v_lshl_add_u64 v[36:37], v[36:37], 0, v[60:61]
	v_cndmask_b32_e64 v33, v213, v33, s[0:1]
	v_lshlrev_b32_e32 v93, 2, v33
	ds_bpermute_b32 v33, v93, v32
	v_lshl_add_u64 v[36:37], v[36:37], 0, v[106:107]
	v_lshl_add_u64 v[36:37], v[36:37], 0, v[108:109]
	global_store_dwordx2 v[36:37], v[38:39], off
	s_waitcnt lgkmcnt(0)
	v_add_f32_e32 v32, v32, v33
	v_xor_b32_e32 v33, 4, v213
	v_cmp_lt_i32_e64 s[0:1], v33, v34
	s_nop 1
	v_cndmask_b32_e64 v33, v213, v33, s[0:1]
	v_lshlrev_b32_e32 v94, 2, v33
	ds_bpermute_b32 v33, v94, v32
	s_waitcnt lgkmcnt(0)
	v_add_f32_e32 v32, v32, v33
	v_xor_b32_e32 v33, 2, v213
	v_cmp_lt_i32_e64 s[0:1], v33, v34
	s_nop 1
	v_cndmask_b32_e64 v33, v213, v33, s[0:1]
	v_lshlrev_b32_e32 v95, 2, v33
	ds_bpermute_b32 v33, v95, v32
	s_waitcnt lgkmcnt(0)
	v_add_f32_e32 v32, v32, v33
	v_xor_b32_e32 v33, 1, v213
	v_cmp_lt_i32_e64 s[0:1], v33, v34
	s_nop 1
	v_cndmask_b32_e64 v33, v213, v33, s[0:1]
	v_lshlrev_b32_e32 v107, 2, v33
	ds_bpermute_b32 v33, v107, v32
	s_and_saveexec_b64 s[0:1], vcc
	s_cbranch_execz .LBB0_150
	s_waitcnt lgkmcnt(0)
	v_add_f32_e32 v32, v32, v33
	v_fma_f32 v32, v32, s75, 0.5
	v_cvt_u32_f32_e32 v34, v32
	v_lshl_add_u64 v[32:33], v[186:187], 2, s[8:9]
	global_atomic_add v[32:33], v34, off

.Lchk_skip:
	s_load_dword s98, s[96:97], 0x0
	s_waitcnt lgkmcnt(0)
	s_cmp_eq_u32 s98, 0x200
	s_cbranch_scc0 .LBB0_509
	s_add_i32 s99, s6, -3
	s_cmp_lt_i32 s99, 0
	s_cbranch_scc1 .LBB0_509
	s_mul_i32 s98, s99, 37
	s_lshr_b32 s98, s98, 8
	s_mul_i32 s98, s98, 7
	s_sub_i32 s99, s99, s98
	s_cmp_eq_u32 s99, 3
	s_cbranch_scc0 .LBB0_509
	s_waitcnt vmcnt(0) lgkmcnt(0)
	s_barrier
	s_mov_b64 s[0:1], 0
	s_branch .Llong21
